# gemm_sample_rows: XCD-aware item mapping (each XCD covers a 4x8 block of 64x64 tiles so its A/B working set fits its L2)
# baseline (speedup 1.0000x reference)
; template <int NH>
; __device__ void gemm_sample_rows(const Params& p, const u16* __restrict__ A, const u16* __restrict__ Bt,
;                                  const float* __restrict__ resid, float* __restrict__ outf, unsigned char* smem, const int rep) {
;   constexpr int K = 2048, RS = 65;
;   float* red = (float*)smem;
;   float* rstdS = red + 8 * 64 * RS;
;   const int tid = (int)p.tidx, lane = tid & 63, w = (int)p.wv, l15 = lane & 15, g = lane >> 4;
;   const float* parts = (const float*)(p.ws + OFF_PARTS);
;   for (int item0 = blockIdx.x; item0 < 256 * rep; item0 += gridDim.x) {
;     const int item = item0 & 255;
;     const int m0 = NPROMPT + (item >> 4) * 64, n0 = (item & 15) * 64;
;     for (int idx = tid; idx < 64 * NH; idx += NTHR) {
;       const int row = idx / NH, h = idx % NH;
;       const float* pp = parts + (size_t)(m0 + row) * 64 + h * (64 / NH);
;       float sm = 0.f;
; #pragma unroll
;       for (int q = 0; q < 64 / NH; ++q) sm += pp[q];
;       rstdS[idx] = rsqrtf(sm / (float)(K / NH) + 1e-6f);
;     }
;     f32x4 acc[4][4];
; #pragma unroll
;     for (int i = 0; i < 4; ++i)
; #pragma unroll
;       for (int j = 0; j < 4; ++j) acc[i][j] = (f32x4){0.f, 0.f, 0.f, 0.f};
;     const u16* ap = A + (size_t)(m0 + l15) * K + w * 256 + 8 * g;
;     const u16* bp = Bt + (size_t)(n0 + l15) * K + w * 256 + 8 * g;
;     ...
;       const int h = (w * 256) / (K / NH);
; #pragma unroll
;       for (int mf = 0; mf < 4; ++mf)
; #pragma unroll
;         for (int r = 0; r < 4; ++r) {
;           const int row = mf * 16 + 4 * g + r;
;           const float sc = rstdS[row * NH + h];
; #pragma unroll
;           for (int nf = 0; nf < 4; ++nf) red[(w * 64 + row) * RS + nf * 16 + l15] = acc[mf][nf][r] * sc;
.LBB0_724:
	s_lshl_b32 s14, s24, 8
	s_cmp_ge_i32 s78, s14
	s_waitcnt lgkmcnt(0)
	s_barrier
	s_cbranch_scc1 .LBB0_732
	s_movk_i32 s2, 0x100
	s_lshr_b32 s4, s23, 31
	v_cmp_gt_i32_e32 vcc, s2, v196
	s_lshl_b32 s2, s23, 8
	s_add_i32 s23, s23, s4
	s_lshl_b32 s4, s23, 1
	s_ashr_i32 s3, s2, 31
	s_and_b32 s4, s4, -4
	s_add_i32 s4, s4, 0x20800
	s_lshl_b64 s[2:3], s[2:3], 1
	v_lshlrev_b32_e32 v1, 2, v199
	s_add_u32 s2, s84, s2
	v_lshlrev_b32_e32 v2, 3, v195
	v_or_b32_e32 v5, s22, v1
	s_movk_i32 s5, 0x104
	v_or_b32_e32 v6, 1, v1
	v_or_b32_e32 v8, 2, v1
	v_or_b32_e32 v10, 3, v1
	v_or_b32_e32 v12, 16, v1
	v_or_b32_e32 v14, 17, v1
	v_or_b32_e32 v16, 18, v1
	v_or_b32_e32 v18, 19, v1
	v_or_b32_e32 v20, 32, v1
	v_or_b32_e32 v22, 33, v1
	v_or_b32_e32 v24, 34, v1
	v_or_b32_e32 v26, 35, v1
	v_or_b32_e32 v28, 48, v1
	v_or_b32_e32 v30, 49, v1
	v_or_b32_e32 v32, 50, v1
	v_or_b32_e32 v1, 51, v1
	s_addc_u32 s3, s85, s3
	v_and_b32_e32 v2, 56, v2
	v_lshlrev_b32_e32 v7, 4, v6
	v_or_b32_e32 v6, s22, v6
	v_lshlrev_b32_e32 v9, 4, v8
	v_or_b32_e32 v8, s22, v8
	v_lshlrev_b32_e32 v11, 4, v10
	v_or_b32_e32 v10, s22, v10
	v_lshlrev_b32_e32 v13, 4, v12
	v_or_b32_e32 v12, s22, v12
	v_lshlrev_b32_e32 v15, 4, v14
	v_or_b32_e32 v14, s22, v14
	v_lshlrev_b32_e32 v17, 4, v16
	v_or_b32_e32 v16, s22, v16
	v_lshlrev_b32_e32 v19, 4, v18
	v_or_b32_e32 v18, s22, v18
	v_lshlrev_b32_e32 v21, 4, v20
	v_or_b32_e32 v20, s22, v20
	v_lshlrev_b32_e32 v23, 4, v22
	v_or_b32_e32 v22, s22, v22
	v_lshlrev_b32_e32 v25, 4, v24
	v_or_b32_e32 v24, s22, v24
	v_lshlrev_b32_e32 v27, 4, v26
	v_or_b32_e32 v26, s22, v26
	v_lshlrev_b32_e32 v29, 4, v28
	v_or_b32_e32 v28, s22, v28
	v_lshlrev_b32_e32 v31, 4, v30
	v_or_b32_e32 v30, s22, v30
	v_lshlrev_b32_e32 v33, 4, v32
	v_or_b32_e32 v32, s22, v32
	v_lshlrev_b32_e32 v34, 4, v1
	v_or_b32_e32 v1, s22, v1
	v_mul_lo_u32 v35, v197, s5
	s_add_u32 s0, s2, s0
	v_lshlrev_b32_e32 v3, 2, v0
	v_mov_b32_e32 v181, 0
	v_lshlrev_b32_e32 v4, 6, v199
	v_mul_lo_u32 v5, v5, s5
	v_mul_lo_u32 v6, v6, s5
	v_mul_lo_u32 v8, v8, s5
	v_mul_lo_u32 v10, v10, s5
	v_mul_lo_u32 v12, v12, s5
	v_mul_lo_u32 v14, v14, s5
	v_mul_lo_u32 v16, v16, s5
	v_mul_lo_u32 v18, v18, s5
	v_mul_lo_u32 v20, v20, s5
	v_mul_lo_u32 v22, v22, s5
	v_mul_lo_u32 v24, v24, s5
	v_mul_lo_u32 v26, v26, s5
	v_mul_lo_u32 v28, v28, s5
	v_mul_lo_u32 v30, v30, s5
	v_mul_lo_u32 v32, v32, s5
	v_mul_lo_u32 v1, v1, s5
	v_lshl_add_u32 v70, v2, 2, v35
	s_addc_u32 s1, s3, s1
	v_add_u32_e32 v87, 0x4000, v0
	v_lshlrev_b32_e32 v88, 11, v0
	v_mov_b32_e32 v0, 0x20800
	v_add_u32_e32 v71, 0x10400, v70
	v_add_u32_e32 v72, 0x10408, v70
	v_add_u32_e32 v73, 0x10410, v70
	v_add_u32_e32 v74, 0x10418, v70
	v_add_u32_e32 v75, 0x14500, v70
	v_add_u32_e32 v76, 0x14508, v70
	v_add_u32_e32 v77, 0x14510, v70
	v_add_u32_e32 v78, 0x14518, v70
	v_add_u32_e32 v79, 0x18600, v70
	v_add_u32_e32 v80, 0x18608, v70
	v_add_u32_e32 v81, 0x18610, v70
	v_add_u32_e32 v82, 0x18618, v70
	v_add_u32_e32 v83, 0x1c700, v70
	v_add_u32_e32 v84, 0x1c708, v70
	v_add_u32_e32 v85, 0x1c710, v70
	v_add_u32_e32 v86, 0x1c718, v70
	v_lshl_add_u64 v[64:65], s[0:1], 0, v[180:181]
	s_lshl_b32 s15, s78, 2
	s_lshl_b32 s16, s96, 2
	s_lshl_b32 s17, s78, 6
	s_lshl_b32 s18, s96, 6
	s_mov_b32 s1, 0
	v_mov_b32_e32 v89, 0x358637bd
	s_mov_b32 s19, 0x800000
	s_movk_i32 s20, 0xfeff
	s_mov_b32 s21, 0x11262000
	s_mov_b32 s22, 0x11272000
	s_mov_b32 s23, 0x11282000
	s_mov_b32 s24, 0x11292000
	s_mov_b32 s25, 0xc00000
	s_mov_b32 s26, 0xc10000
	s_mov_b32 s27, 0xc20000
	s_mov_b32 s28, 0xc30000
	v_add_u32_e32 v90, s4, v4
	v_add_u32_e32 v91, v3, v5
	v_add_u32_e32 v92, s4, v7
	v_add_u32_e32 v93, v3, v6
	v_add_u32_e32 v94, s4, v9
	v_add_u32_e32 v95, v3, v8
	v_add_u32_e32 v96, s4, v11
	v_add_u32_e32 v97, v3, v10
	v_add_u32_e32 v98, s4, v13
	v_add_u32_e32 v99, v3, v12
	v_add_u32_e32 v100, s4, v15
	v_add_u32_e32 v101, v3, v14
	v_add_u32_e32 v102, s4, v17
	v_add_u32_e32 v103, v3, v16
	v_add_u32_e32 v104, s4, v19
	v_add_u32_e32 v105, v3, v18
	v_add_u32_e32 v106, s4, v21
	v_add_u32_e32 v107, v3, v20
	v_add_u32_e32 v108, s4, v23
	v_add_u32_e32 v109, v3, v22
	v_add_u32_e32 v110, s4, v25
	v_add_u32_e32 v111, v3, v24
	v_add_u32_e32 v112, s4, v27
	v_add_u32_e32 v113, v3, v26
	v_add_u32_e32 v114, s4, v29
	v_add_u32_e32 v115, v3, v28
	v_add_u32_e32 v116, s4, v31
	v_add_u32_e32 v117, v3, v30
	v_add_u32_e32 v118, s4, v33
	v_add_u32_e32 v119, v3, v32
	v_add_u32_e32 v120, s4, v34
	v_add_u32_e32 v121, v3, v1
	v_lshlrev_b32_e32 v180, 2, v2
	v_lshl_add_u32 v122, v196, 2, v0
	s_mov_b32 s29, s78
	s_cmp_lg_u32 s96, 0x100
	s_cbranch_scc1 .Lsrmap3
	s_and_b32 s0, s78, 7
	s_lshr_b32 s2, s78, 3
	s_lshr_b32 s29, s0, 1
	s_lshl_b32 s29, s29, 2
	s_lshr_b32 s3, s2, 3
	s_add_i32 s29, s29, s3
	s_lshl_b32 s29, s29, 4
	s_and_b32 s0, s0, 1
	s_lshl_b32 s0, s0, 3
	s_and_b32 s2, s2, 7
	s_add_i32 s0, s0, s2
	s_add_i32 s29, s29, s0
	s_lshl_b32 s15, s29, 2
	s_lshl_b32 s17, s29, 6
.Lsrmap3:
.LBB0_726:
	s_lshl_b32 s0, s29, 2
	s_and_b32 s0, s0, 0x3c0
	s_or_b32 s30, s0, 0x4000
	s_and_saveexec_b64 s[4:5], vcc
	s_cbranch_execz .LBB0_729
	s_mov_b64 s[8:9], 0
	v_mov_b32_e32 v0, v122
	v_mov_b32_e32 v1, v198
	v_mov_b32_e32 v2, v196

; template <int NH>
; __device__ void gemm_sample_rows(const Params& p, const u16* __restrict__ A, const u16* __restrict__ Bt,
;                                  const float* __restrict__ resid, float* __restrict__ outf, unsigned char* smem, const int rep) {
;   constexpr int K = 2048, RS = 65;
;   float* red = (float*)smem;
;   float* rstdS = red + 8 * 64 * RS;
;   const int tid = (int)p.tidx, lane = tid & 63, w = (int)p.wv, l15 = lane & 15, g = lane >> 4;
;   const float* parts = (const float*)(p.ws + OFF_PARTS);
;   for (int item0 = blockIdx.x; item0 < 256 * rep; item0 += gridDim.x) {
;     const int item = item0 & 255;
;     const int m0 = NPROMPT + (item >> 4) * 64, n0 = (item & 15) * 64;
;     for (int idx = tid; idx < 64 * NH; idx += NTHR) {
;       const int row = idx / NH, h = idx % NH;
;       const float* pp = parts + (size_t)(m0 + row) * 64 + h * (64 / NH);
;       float sm = 0.f;
; #pragma unroll
;       for (int q = 0; q < 64 / NH; ++q) sm += pp[q];
;       rstdS[idx] = rsqrtf(sm / (float)(K / NH) + 1e-6f);
;     }
;     f32x4 acc[4][4];
; #pragma unroll
;     for (int i = 0; i < 4; ++i)
; #pragma unroll
;       for (int j = 0; j < 4; ++j) acc[i][j] = (f32x4){0.f, 0.f, 0.f, 0.f};
;     const u16* ap = A + (size_t)(m0 + l15) * K + w * 256 + 8 * g;
;     const u16* bp = Bt + (size_t)(n0 + l15) * K + w * 256 + 8 * g;
;     ...
;       const int h = (w * 256) / (K / NH);
; #pragma unroll
;       for (int mf = 0; mf < 4; ++mf)
; #pragma unroll
;         for (int r = 0; r < 4; ++r) {
;           const int row = mf * 16 + 4 * g + r;
;           const float sc = rstdS[row * NH + h];
; #pragma unroll
;           for (int nf = 0; nf < 4; ++nf) red[(w * 64 + row) * RS + nf * 16 + l15] = acc[mf][nf][r] * sc;
.LBB0_2029:
	s_lshl_b32 s12, s22, 8
	s_cmp_ge_i32 s78, s12
	s_barrier
	s_cbranch_scc1 .LBB0_2037
	s_movk_i32 s2, 0x200
	v_cmp_gt_i32_e32 vcc, s2, v196
	s_lshl_b32 s2, s21, 8
	s_ashr_i32 s3, s2, 31
	s_lshl_b32 s4, s21, 2
	s_add_i32 s4, s4, 0x20800
	s_lshl_b64 s[2:3], s[2:3], 1
	v_lshlrev_b32_e32 v1, 2, v199
	s_add_u32 s2, s84, s2
	v_lshlrev_b32_e32 v3, 3, v195
	v_or_b32_e32 v4, s20, v1
	s_movk_i32 s5, 0x104
	v_or_b32_e32 v5, 1, v1
	v_or_b32_e32 v7, 2, v1
	v_or_b32_e32 v9, 3, v1
	v_or_b32_e32 v11, 16, v1
	v_or_b32_e32 v13, 17, v1
	v_or_b32_e32 v15, 18, v1
	v_or_b32_e32 v17, 19, v1
	v_or_b32_e32 v19, 32, v1
	v_or_b32_e32 v21, 33, v1
	v_or_b32_e32 v23, 34, v1
	v_or_b32_e32 v25, 35, v1
	v_or_b32_e32 v27, 48, v1
	v_or_b32_e32 v29, 49, v1
	v_or_b32_e32 v31, 50, v1
	v_or_b32_e32 v1, 51, v1
	s_addc_u32 s3, s85, s3
	v_and_b32_e32 v64, 56, v3
	v_lshlrev_b32_e32 v6, 5, v5
	v_or_b32_e32 v5, s20, v5
	v_lshlrev_b32_e32 v8, 5, v7
	v_or_b32_e32 v7, s20, v7
	v_lshlrev_b32_e32 v10, 5, v9
	v_or_b32_e32 v9, s20, v9
	v_lshlrev_b32_e32 v12, 5, v11
	v_or_b32_e32 v11, s20, v11
	v_lshlrev_b32_e32 v14, 5, v13
	v_or_b32_e32 v13, s20, v13
	v_lshlrev_b32_e32 v16, 5, v15
	v_or_b32_e32 v15, s20, v15
	v_lshlrev_b32_e32 v18, 5, v17
	v_or_b32_e32 v17, s20, v17
	s_waitcnt vmcnt(0)
	v_lshlrev_b32_e32 v20, 5, v19
	v_or_b32_e32 v19, s20, v19
	v_lshlrev_b32_e32 v22, 5, v21
	v_or_b32_e32 v21, s20, v21
	v_lshlrev_b32_e32 v24, 5, v23
	v_or_b32_e32 v23, s20, v23
	v_lshlrev_b32_e32 v26, 5, v25
	v_or_b32_e32 v25, s20, v25
	v_lshlrev_b32_e32 v28, 5, v27
	v_or_b32_e32 v27, s20, v27
	v_lshlrev_b32_e32 v30, 5, v29
	v_or_b32_e32 v29, s20, v29
	v_lshlrev_b32_e32 v32, 5, v31
	v_or_b32_e32 v31, s20, v31
	v_lshlrev_b32_e32 v33, 5, v1
	v_or_b32_e32 v1, s20, v1
	v_mul_lo_u32 v34, v197, s5
	s_add_u32 s0, s2, s0
	v_lshlrev_b32_e32 v2, 2, v0
	v_mov_b32_e32 v181, 0
	v_lshlrev_b32_e32 v3, 7, v199
	v_mul_lo_u32 v4, v4, s5
	v_mul_lo_u32 v5, v5, s5
	v_mul_lo_u32 v7, v7, s5
	v_mul_lo_u32 v9, v9, s5
	v_mul_lo_u32 v11, v11, s5
	v_mul_lo_u32 v13, v13, s5
	v_mul_lo_u32 v15, v15, s5
	v_mul_lo_u32 v17, v17, s5
	v_mul_lo_u32 v19, v19, s5
	v_mul_lo_u32 v21, v21, s5
	v_mul_lo_u32 v23, v23, s5
	v_mul_lo_u32 v25, v25, s5
	v_mul_lo_u32 v27, v27, s5
	v_mul_lo_u32 v29, v29, s5
	v_mul_lo_u32 v31, v31, s5
	v_mul_lo_u32 v1, v1, s5
	v_lshl_add_u32 v65, v64, 2, v34
	s_addc_u32 s1, s3, s1
	v_add_u32_e32 v88, 0x4000, v0
	v_lshlrev_b32_e32 v89, 11, v0
	v_mov_b32_e32 v0, 0x20800
	v_add_u32_e32 v72, 0x10400, v65
	v_add_u32_e32 v73, 0x10408, v65
	v_add_u32_e32 v74, 0x10410, v65
	v_add_u32_e32 v75, 0x10418, v65
	v_add_u32_e32 v76, 0x14500, v65
	v_add_u32_e32 v77, 0x14508, v65
	v_add_u32_e32 v78, 0x14510, v65
	v_add_u32_e32 v79, 0x14518, v65
	v_add_u32_e32 v80, 0x18600, v65
	v_add_u32_e32 v81, 0x18608, v65
	v_add_u32_e32 v82, 0x18610, v65
	v_add_u32_e32 v83, 0x18618, v65
	v_add_u32_e32 v84, 0x1c700, v65
	v_add_u32_e32 v85, 0x1c708, v65
	v_add_u32_e32 v86, 0x1c710, v65
	v_add_u32_e32 v87, 0x1c718, v65
	v_lshl_add_u64 v[66:67], s[0:1], 0, v[180:181]
	s_lshl_b32 s13, s78, 2
	s_lshl_b32 s14, s96, 2
	s_lshl_b32 s15, s78, 6
	s_lshl_b32 s16, s96, 6
	v_mov_b32_e32 v90, 0x358637bd
	s_mov_b32 s17, 0x800000
	s_mov_b32 s18, 0x11262000
	s_mov_b32 s19, 0x11272000
	s_mov_b32 s20, 0x11282000
	s_mov_b32 s21, 0x11292000
	s_mov_b32 s22, 0x1c40000
	s_mov_b32 s23, 0x1c50000
	s_mov_b32 s24, 0x1c60000
	s_mov_b32 s25, 0x1c70000
	v_add_u32_e32 v91, s4, v3
	v_add_u32_e32 v92, v2, v4
	v_add_u32_e32 v93, s4, v6
	v_add_u32_e32 v94, v2, v5
	v_add_u32_e32 v95, s4, v8
	v_add_u32_e32 v96, v2, v7
	v_add_u32_e32 v97, s4, v10
	v_add_u32_e32 v98, v2, v9
	v_add_u32_e32 v99, s4, v12
	v_add_u32_e32 v100, v2, v11
	v_add_u32_e32 v101, s4, v14
	v_add_u32_e32 v102, v2, v13
	v_add_u32_e32 v103, s4, v16
	v_add_u32_e32 v104, v2, v15
	v_add_u32_e32 v105, s4, v18
	v_add_u32_e32 v106, v2, v17
	v_add_u32_e32 v107, s4, v20
	v_add_u32_e32 v108, v2, v19
	v_add_u32_e32 v109, s4, v22
	v_add_u32_e32 v110, v2, v21
	v_add_u32_e32 v111, s4, v24
	v_add_u32_e32 v112, v2, v23
	v_add_u32_e32 v113, s4, v26
	v_add_u32_e32 v114, v2, v25
	v_add_u32_e32 v115, s4, v28
	v_add_u32_e32 v116, v2, v27
	v_add_u32_e32 v117, s4, v30
	v_add_u32_e32 v118, v2, v29
	v_add_u32_e32 v119, s4, v32
	v_add_u32_e32 v120, v2, v31
	v_add_u32_e32 v121, s4, v33
	v_add_u32_e32 v122, v2, v1
	v_lshl_add_u32 v123, v196, 2, v0
	s_mov_b32 s26, s78
	s_cmp_lg_u32 s96, 0x100
	s_cbranch_scc1 .Lsrmap8
	s_and_b32 s0, s78, 7
	s_lshr_b32 s1, s78, 3
	s_lshr_b32 s26, s0, 1
	s_lshl_b32 s26, s26, 2
	s_lshr_b32 s27, s1, 3
	s_add_i32 s26, s26, s27
	s_lshl_b32 s26, s26, 4
	s_and_b32 s0, s0, 1
	s_lshl_b32 s0, s0, 3
	s_and_b32 s1, s1, 7
	s_add_i32 s0, s0, s1
	s_add_i32 s26, s26, s0
	s_lshl_b32 s13, s26, 2
	s_lshl_b32 s15, s26, 6
.Lsrmap8:
.LBB0_2031:
	s_lshl_b32 s0, s26, 2
	s_and_b32 s27, s0, 0x3c0
	s_bitset1_b32 s27, 14
	s_and_saveexec_b64 s[0:1], vcc
	s_cbranch_execz .LBB0_2034
	s_mov_b64 s[4:5], 0
	v_mov_b32_e32 v0, v123
	v_mov_b32_e32 v1, v198
	v_mov_b32_e32 v2, v196
